# GEMM K-loops: removed the redundant mid-segment s_setprio 0/1 pair between the two 16-MFMA blocks (on top of v36)
# speedup vs baseline: 1.0089x; 1.0089x over previous
; #define PG8_STAGE(bufoff, gbase, voff) do { _Pragma("unroll") for (int _i = 0; _i < 2; ++_i) \
;         __builtin_amdgcn_global_load_lds((const unsigned*)((const char*)(gbase) + (voff)[_i]), (PG8_LAS unsigned*)(lds + (bufoff) + ldsw + _i * 8192), 16, 0, 0); } while (0)
; #define PG8_LDA(dst, b, h) do { _Pragma("unroll") for (int m = 0; m < 4; ++m) _Pragma("unroll") for (int k = 0; k < 2; ++k) dst[m][k] = *(const PG8_LAS bf16x8*)(lds + PG8_SA(b, h) + aoff + m * 2048 + k * 1024); } while (0)
; #define PG8_LDB(dst, b, h) do { _Pragma("unroll") for (int n = 0; n < 2; ++n) _Pragma("unroll") for (int k = 0; k < 2; ++k) dst[n][k] = *(const PG8_LAS bf16x8*)(lds + PG8_SB(b, h) + boff + n * 2048 + k * 1024); } while (0)
; #define PG8_MMA(ai, bj, At, Bt) do { __builtin_amdgcn_s_setprio(1); _Pragma("unroll") for (int m = 0; m < 4; ++m) _Pragma("unroll") for (int n = 0; n < 2; ++n) _Pragma("unroll") for (int k = 0; k < 2; ++k) \
;         acc[ai][bj][m][n] = __builtin_amdgcn_mfma_f32_16x16x32_bf16(Bt[n][k], At[m][k], acc[ai][bj][m][n], 0, 0, 0); __builtin_amdgcn_s_setprio(0); } while (0)
; #define PG8_WAIT_V(n) asm volatile("s_waitcnt vmcnt(" #n ")" ::: "memory")
; #define PG8_WAIT_L(n) asm volatile("s_waitcnt lgkmcnt(" #n ")" ::: "memory")
; #define PG8_BAR __builtin_amdgcn_s_barrier()
; #define PG8_SCHED __builtin_amdgcn_sched_barrier(0)
; template <class Epi, class Sched, bool ALIGN_EPI = false, bool SP2 = false>
; __device__ __forceinline__ void gemm_phase(PG8_LAS unsigned char* lds, const Gemm g, const Sched& S, const Epi& E, const int tid_in) {
;     ...
;             PG8_LDB(B0, 0, 0); PG8_LDB(B1, 0, 1); PG8_SCHED; PG8_LDA(At, 0, 0); PG8_STAGE(PG8_SA(1, 1), a1 + hstep, voffA);
;             PG8_WAIT_V(8); PG8_WAIT_L(0); PG8_BAR; PG8_MMA(0, 0, At, B0); PG8_MMA(0, 1, At, B1); PG8_BAR; PG8_SCHED;
;             PG8_LDA(At, 0, 1); PG8_STAGE(PG8_SB(0, 0), b2, voffB); PG8_STAGE(PG8_SB(0, 1), b2 + hstep, voffB); PG8_STAGE(PG8_SA(0, 0), a2, voffA);
.LBB0_42:
	s_add_u32 s10, s4, 0xfffc0080
	s_addc_u32 s11, s5, -1
	s_add_i32 s61, 0, 0x10000
	s_cmp_eq_u32 s60, 12
	s_cselect_b32 s13, s14, s11
	s_cselect_b32 s12, s15, s10
	s_cselect_b32 s11, s23, s59
	s_cselect_b32 s10, s25, s58
	s_add_i32 s64, 0, 0x14000
	s_waitcnt vmcnt(0)
	v_add_u32_e32 v76, s61, v162
	v_add_u32_e32 v160, s64, v162
	ds_read_b128 v[56:59], v76
	ds_read_b128 v[64:67], v76 offset:1024
	ds_read_b128 v[68:71], v76 offset:2048
	ds_read_b128 v[76:79], v76 offset:3072
	ds_read_b128 v[170:173], v160
	ds_read_b128 v[174:177], v160 offset:1024
	ds_read_b128 v[178:181], v160 offset:2048
	ds_read_b128 v[182:185], v160 offset:3072
	v_lshl_add_u64 v[160:161], s[4:5], 0, v[156:157]
	s_add_i32 m0, s48, 0xc000
	ds_read_b128 v[186:189], v168
	ds_read_b128 v[200:203], v168 offset:1024
	ds_read_b128 v[204:207], v168 offset:2048
	ds_read_b128 v[208:211], v168 offset:3072
	ds_read_b128 v[212:215], v168 offset:4096
	ds_read_b128 v[234:237], v168 offset:5120
	ds_read_b128 v[238:241], v168 offset:6144
	ds_read_b128 v[242:245], v168 offset:7168
	global_load_lds_dwordx4 v[160:161], off
	v_lshl_add_u64 v[160:161], s[4:5], 0, v[158:159]
	s_add_i32 m0, s48, 0xe000
	s_nop 0
	global_load_lds_dwordx4 v[160:161], off
	s_waitcnt vmcnt(8)
	s_waitcnt lgkmcnt(0)
	s_barrier
	s_setprio 1
	s_waitcnt lgkmcnt(0)
	v_mfma_f32_16x16x32_bf16 v[140:143], v[56:59], v[186:189], v[140:143]
	v_mfma_f32_16x16x32_bf16 v[136:139], v[68:71], v[186:189], v[136:139]
	v_mfma_f32_16x16x32_bf16 v[124:127], v[56:59], v[204:207], v[124:127]
	v_mfma_f32_16x16x32_bf16 v[120:123], v[68:71], v[204:207], v[120:123]
	v_mfma_f32_16x16x32_bf16 v[108:111], v[56:59], v[212:215], v[108:111]
	v_mfma_f32_16x16x32_bf16 v[104:107], v[68:71], v[212:215], v[104:107]
	v_mfma_f32_16x16x32_bf16 v[92:95], v[56:59], v[238:241], v[92:95]
	v_mfma_f32_16x16x32_bf16 v[88:91], v[68:71], v[238:241], v[88:91]
	v_mfma_f32_16x16x32_bf16 v[140:143], v[64:67], v[200:203], v[140:143]
	v_mfma_f32_16x16x32_bf16 v[136:139], v[76:79], v[200:203], v[136:139]
	v_mfma_f32_16x16x32_bf16 v[124:127], v[64:67], v[208:211], v[124:127]
	v_mfma_f32_16x16x32_bf16 v[120:123], v[76:79], v[208:211], v[120:123]
	v_mfma_f32_16x16x32_bf16 v[108:111], v[64:67], v[234:237], v[108:111]
	v_mfma_f32_16x16x32_bf16 v[104:107], v[76:79], v[234:237], v[104:107]
	v_mfma_f32_16x16x32_bf16 v[92:95], v[64:67], v[242:245], v[92:95]
	v_mfma_f32_16x16x32_bf16 v[88:91], v[76:79], v[242:245], v[88:91]
	v_mfma_f32_16x16x32_bf16 v[132:135], v[170:173], v[186:189], v[132:135]
	v_mfma_f32_16x16x32_bf16 v[128:131], v[178:181], v[186:189], v[128:131]
	v_mfma_f32_16x16x32_bf16 v[116:119], v[170:173], v[204:207], v[116:119]
	v_mfma_f32_16x16x32_bf16 v[112:115], v[178:181], v[204:207], v[112:115]
	v_mfma_f32_16x16x32_bf16 v[100:103], v[170:173], v[212:215], v[100:103]
	v_mfma_f32_16x16x32_bf16 v[96:99], v[178:181], v[212:215], v[96:99]
	v_mfma_f32_16x16x32_bf16 v[84:87], v[170:173], v[238:241], v[84:87]
	v_mfma_f32_16x16x32_bf16 v[80:83], v[178:181], v[238:241], v[80:83]
	v_mfma_f32_16x16x32_bf16 v[132:135], v[174:177], v[200:203], v[132:135]
	v_mfma_f32_16x16x32_bf16 v[128:131], v[182:185], v[200:203], v[128:131]
	v_mfma_f32_16x16x32_bf16 v[116:119], v[174:177], v[208:211], v[116:119]
	v_mfma_f32_16x16x32_bf16 v[112:115], v[182:185], v[208:211], v[112:115]
	v_mfma_f32_16x16x32_bf16 v[100:103], v[174:177], v[234:237], v[100:103]
	v_mfma_f32_16x16x32_bf16 v[96:99], v[182:185], v[234:237], v[96:99]
	v_mfma_f32_16x16x32_bf16 v[84:87], v[174:177], v[242:245], v[84:87]
	v_mfma_f32_16x16x32_bf16 v[80:83], v[182:185], v[242:245], v[80:83]
	s_setprio 0
	s_barrier
	s_add_i32 s61, s61, s41
	v_lshl_add_u64 v[160:161], s[10:11], 0, v[148:149]
	s_mov_b32 m0, s61
	ds_read_b128 v[186:189], v168 offset:16384
	ds_read_b128 v[200:203], v168 offset:17408
	ds_read_b128 v[204:207], v168 offset:18432
	ds_read_b128 v[208:211], v168 offset:19456
	ds_read_b128 v[212:215], v168 offset:20480
	ds_read_b128 v[234:237], v168 offset:21504
	ds_read_b128 v[238:241], v168 offset:22528
	ds_read_b128 v[242:245], v168 offset:23552
	global_load_lds_dwordx4 v[160:161], off
	s_add_i32 m0, s61, 0x2000
	s_add_u32 s62, s10, 0x40000
	v_lshl_add_u64 v[190:191], s[10:11], 0, v[144:145]
	s_addc_u32 s63, s11, 0
	s_add_i32 s61, s64, s41
	global_load_lds_dwordx4 v[190:191], off
	v_lshl_add_u64 v[218:219], s[62:63], 0, v[148:149]
	s_mov_b32 m0, s61
	v_lshl_add_u64 v[220:221], s[12:13], 0, v[146:147]
	global_load_lds_dwordx4 v[218:219], off
	v_lshl_add_u64 v[218:219], s[62:63], 0, v[144:145]
	s_add_i32 m0, s61, 0x2000
	s_nop 0
	global_load_lds_dwordx4 v[218:219], off
	v_lshl_add_u64 v[218:219], s[12:13], 0, v[150:151]
	s_mov_b32 m0, s48
	s_nop 0
	global_load_lds_dwordx4 v[218:219], off
	s_mov_b32 m0, s49
	s_nop 0
	global_load_lds_dwordx4 v[220:221], off
	s_waitcnt vmcnt(8)
	s_waitcnt lgkmcnt(0)
	s_barrier
; #define PG8_STAGE(bufoff, gbase, voff) do { _Pragma("unroll") for (int _i = 0; _i < 2; ++_i) \
;         __builtin_amdgcn_global_load_lds((const unsigned*)((const char*)(gbase) + (voff)[_i]), (PG8_LAS unsigned*)(lds + (bufoff) + ldsw + _i * 8192), 16, 0, 0); } while (0)
; #define PG8_LDA(dst, b, h) do { _Pragma("unroll") for (int m = 0; m < 4; ++m) _Pragma("unroll") for (int k = 0; k < 2; ++k) dst[m][k] = *(const PG8_LAS bf16x8*)(lds + PG8_SA(b, h) + aoff + m * 2048 + k * 1024); } while (0)
; #define PG8_LDB(dst, b, h) do { _Pragma("unroll") for (int n = 0; n < 2; ++n) _Pragma("unroll") for (int k = 0; k < 2; ++k) dst[n][k] = *(const PG8_LAS bf16x8*)(lds + PG8_SB(b, h) + boff + n * 2048 + k * 1024); } while (0)
; #define PG8_MMA(ai, bj, At, Bt) do { __builtin_amdgcn_s_setprio(1); _Pragma("unroll") for (int m = 0; m < 4; ++m) _Pragma("unroll") for (int n = 0; n < 2; ++n) _Pragma("unroll") for (int k = 0; k < 2; ++k) \
;         acc[ai][bj][m][n] = __builtin_amdgcn_mfma_f32_16x16x32_bf16(Bt[n][k], At[m][k], acc[ai][bj][m][n], 0, 0, 0); __builtin_amdgcn_s_setprio(0); } while (0)
; #define PG8_WAIT_V(n) asm volatile("s_waitcnt vmcnt(" #n ")" ::: "memory")
; #define PG8_WAIT_L(n) asm volatile("s_waitcnt lgkmcnt(" #n ")" ::: "memory")
; #define PG8_BAR __builtin_amdgcn_s_barrier()
; #define PG8_SCHED __builtin_amdgcn_sched_barrier(0)
; template <class Epi, class Sched, bool ALIGN_EPI = false, bool SP2 = false>
; __device__ __forceinline__ void gemm_phase(PG8_LAS unsigned char* lds, const Gemm g, const Sched& S, const Epi& E, const int tid_in) {
;     ...
;             PG8_WAIT_V(8); PG8_WAIT_L(0); PG8_BAR; PG8_MMA(1, 0, At, B0); PG8_MMA(1, 1, At, B1); PG8_BAR; PG8_SCHED;
;             PG8_LDB(B0, 1, 0); PG8_LDB(B1, 1, 1); PG8_SCHED; PG8_LDA(At, 1, 0); PG8_STAGE(PG8_SA(0, 1), a2 + hstep, voffA);
;             PG8_WAIT_V(8); PG8_WAIT_L(0); PG8_BAR; PG8_MMA(0, 0, At, B0); PG8_MMA(0, 1, At, B1); PG8_BAR; PG8_SCHED;
	s_setprio 1
	s_waitcnt lgkmcnt(0)
	v_mfma_f32_16x16x32_bf16 v[72:75], v[56:59], v[186:189], v[72:75]
	v_mfma_f32_16x16x32_bf16 v[60:63], v[68:71], v[186:189], v[60:63]
	v_mfma_f32_16x16x32_bf16 v[44:47], v[56:59], v[204:207], v[44:47]
	v_mfma_f32_16x16x32_bf16 v[40:43], v[68:71], v[204:207], v[40:43]
	v_mfma_f32_16x16x32_bf16 v[28:31], v[56:59], v[212:215], v[28:31]
	v_mfma_f32_16x16x32_bf16 v[24:27], v[68:71], v[212:215], v[24:27]
	v_mfma_f32_16x16x32_bf16 v[12:15], v[56:59], v[238:241], v[12:15]
	v_mfma_f32_16x16x32_bf16 v[8:11], v[68:71], v[238:241], v[8:11]
	v_mfma_f32_16x16x32_bf16 v[72:75], v[64:67], v[200:203], v[72:75]
	v_mfma_f32_16x16x32_bf16 v[60:63], v[76:79], v[200:203], v[60:63]
	v_mfma_f32_16x16x32_bf16 v[44:47], v[64:67], v[208:211], v[44:47]
	v_mfma_f32_16x16x32_bf16 v[40:43], v[76:79], v[208:211], v[40:43]
	v_mfma_f32_16x16x32_bf16 v[28:31], v[64:67], v[234:237], v[28:31]
	v_mfma_f32_16x16x32_bf16 v[24:27], v[76:79], v[234:237], v[24:27]
	v_mfma_f32_16x16x32_bf16 v[12:15], v[64:67], v[242:245], v[12:15]
	v_mfma_f32_16x16x32_bf16 v[8:11], v[76:79], v[242:245], v[8:11]
	v_mfma_f32_16x16x32_bf16 v[52:55], v[170:173], v[186:189], v[52:55]
	v_mfma_f32_16x16x32_bf16 v[48:51], v[178:181], v[186:189], v[48:51]
	v_mfma_f32_16x16x32_bf16 v[36:39], v[170:173], v[204:207], v[36:39]
	v_mfma_f32_16x16x32_bf16 v[32:35], v[178:181], v[204:207], v[32:35]
	v_mfma_f32_16x16x32_bf16 v[20:23], v[170:173], v[212:215], v[20:23]
	v_mfma_f32_16x16x32_bf16 v[16:19], v[178:181], v[212:215], v[16:19]
	v_mfma_f32_16x16x32_bf16 v[4:7], v[170:173], v[238:241], v[4:7]
	v_mfma_f32_16x16x32_bf16 v[0:3], v[178:181], v[238:241], v[0:3]
	v_mfma_f32_16x16x32_bf16 v[52:55], v[174:177], v[200:203], v[52:55]
	v_mfma_f32_16x16x32_bf16 v[48:51], v[182:185], v[200:203], v[48:51]
	v_mfma_f32_16x16x32_bf16 v[36:39], v[174:177], v[208:211], v[36:39]
	v_mfma_f32_16x16x32_bf16 v[32:35], v[182:185], v[208:211], v[32:35]
	v_mfma_f32_16x16x32_bf16 v[20:23], v[174:177], v[234:237], v[20:23]
	v_mfma_f32_16x16x32_bf16 v[16:19], v[182:185], v[234:237], v[16:19]
	v_mfma_f32_16x16x32_bf16 v[4:7], v[174:177], v[242:245], v[4:7]
	v_mfma_f32_16x16x32_bf16 v[0:3], v[182:185], v[242:245], v[0:3]
	s_setprio 0
	s_barrier
	s_add_i32 s61, 0, 0x18000
	s_add_i32 s62, 0, 0x1c000
	v_add_u32_e32 v76, s61, v162
	v_add_u32_e32 v169, s62, v162
	ds_read_b128 v[56:59], v76
	ds_read_b128 v[64:67], v76 offset:1024
	ds_read_b128 v[68:71], v76 offset:2048
	ds_read_b128 v[76:79], v76 offset:3072
	ds_read_b128 v[170:173], v169
	ds_read_b128 v[174:177], v169 offset:1024
	ds_read_b128 v[178:181], v169 offset:2048
	ds_read_b128 v[182:185], v169 offset:3072
	s_add_u32 s12, s12, 0x40000
	s_addc_u32 s13, s13, 0
	s_mov_b32 m0, s50
	v_lshl_add_u64 v[230:231], s[12:13], 0, v[150:151]
	ds_read_b128 v[186:189], v168 offset:32768
	ds_read_b128 v[200:203], v168 offset:33792
	ds_read_b128 v[204:207], v168 offset:34816
	ds_read_b128 v[208:211], v168 offset:35840
	ds_read_b128 v[212:215], v168 offset:36864
	ds_read_b128 v[234:237], v168 offset:37888
	ds_read_b128 v[238:241], v168 offset:38912
	ds_read_b128 v[242:245], v168 offset:39936
	global_load_lds_dwordx4 v[230:231], off
	v_lshl_add_u64 v[230:231], s[12:13], 0, v[146:147]
	s_mov_b32 m0, s51
	s_nop 0
	global_load_lds_dwordx4 v[230:231], off
	s_waitcnt vmcnt(8)
	s_waitcnt lgkmcnt(0)
	s_barrier
	s_setprio 1
	s_waitcnt lgkmcnt(0)
	v_mfma_f32_16x16x32_bf16 v[140:143], v[56:59], v[186:189], v[140:143]
	v_mfma_f32_16x16x32_bf16 v[136:139], v[68:71], v[186:189], v[136:139]
	v_mfma_f32_16x16x32_bf16 v[124:127], v[56:59], v[204:207], v[124:127]
	v_mfma_f32_16x16x32_bf16 v[120:123], v[68:71], v[204:207], v[120:123]
	v_mfma_f32_16x16x32_bf16 v[108:111], v[56:59], v[212:215], v[108:111]
	v_mfma_f32_16x16x32_bf16 v[104:107], v[68:71], v[212:215], v[104:107]
	v_mfma_f32_16x16x32_bf16 v[92:95], v[56:59], v[238:241], v[92:95]
	v_mfma_f32_16x16x32_bf16 v[88:91], v[68:71], v[238:241], v[88:91]
	v_mfma_f32_16x16x32_bf16 v[140:143], v[64:67], v[200:203], v[140:143]
	v_mfma_f32_16x16x32_bf16 v[136:139], v[76:79], v[200:203], v[136:139]
	v_mfma_f32_16x16x32_bf16 v[124:127], v[64:67], v[208:211], v[124:127]
	v_mfma_f32_16x16x32_bf16 v[120:123], v[76:79], v[208:211], v[120:123]
	v_mfma_f32_16x16x32_bf16 v[108:111], v[64:67], v[234:237], v[108:111]
	v_mfma_f32_16x16x32_bf16 v[104:107], v[76:79], v[234:237], v[104:107]
	v_mfma_f32_16x16x32_bf16 v[92:95], v[64:67], v[242:245], v[92:95]
	v_mfma_f32_16x16x32_bf16 v[88:91], v[76:79], v[242:245], v[88:91]
	v_mfma_f32_16x16x32_bf16 v[132:135], v[170:173], v[186:189], v[132:135]
	v_mfma_f32_16x16x32_bf16 v[128:131], v[178:181], v[186:189], v[128:131]
	v_mfma_f32_16x16x32_bf16 v[116:119], v[170:173], v[204:207], v[116:119]
	v_mfma_f32_16x16x32_bf16 v[112:115], v[178:181], v[204:207], v[112:115]
	v_mfma_f32_16x16x32_bf16 v[100:103], v[170:173], v[212:215], v[100:103]
	v_mfma_f32_16x16x32_bf16 v[96:99], v[178:181], v[212:215], v[96:99]
	v_mfma_f32_16x16x32_bf16 v[84:87], v[170:173], v[238:241], v[84:87]
	v_mfma_f32_16x16x32_bf16 v[80:83], v[178:181], v[238:241], v[80:83]
	v_mfma_f32_16x16x32_bf16 v[132:135], v[174:177], v[200:203], v[132:135]
	v_mfma_f32_16x16x32_bf16 v[128:131], v[182:185], v[200:203], v[128:131]
	v_mfma_f32_16x16x32_bf16 v[116:119], v[174:177], v[208:211], v[116:119]
	v_mfma_f32_16x16x32_bf16 v[112:115], v[182:185], v[208:211], v[112:115]
	v_mfma_f32_16x16x32_bf16 v[100:103], v[174:177], v[234:237], v[100:103]
	v_mfma_f32_16x16x32_bf16 v[96:99], v[182:185], v[234:237], v[96:99]
	v_mfma_f32_16x16x32_bf16 v[84:87], v[174:177], v[242:245], v[84:87]
	v_mfma_f32_16x16x32_bf16 v[80:83], v[182:185], v[242:245], v[80:83]
	s_setprio 0
	s_barrier
; #define PG8_STAGE(bufoff, gbase, voff) do { _Pragma("unroll") for (int _i = 0; _i < 2; ++_i) \
;         __builtin_amdgcn_global_load_lds((const unsigned*)((const char*)(gbase) + (voff)[_i]), (PG8_LAS unsigned*)(lds + (bufoff) + ldsw + _i * 8192), 16, 0, 0); } while (0)
; #define PG8_LDA(dst, b, h) do { _Pragma("unroll") for (int m = 0; m < 4; ++m) _Pragma("unroll") for (int k = 0; k < 2; ++k) dst[m][k] = *(const PG8_LAS bf16x8*)(lds + PG8_SA(b, h) + aoff + m * 2048 + k * 1024); } while (0)
; #define PG8_MMA(ai, bj, At, Bt) do { __builtin_amdgcn_s_setprio(1); _Pragma("unroll") for (int m = 0; m < 4; ++m) _Pragma("unroll") for (int n = 0; n < 2; ++n) _Pragma("unroll") for (int k = 0; k < 2; ++k) \
;         acc[ai][bj][m][n] = __builtin_amdgcn_mfma_f32_16x16x32_bf16(Bt[n][k], At[m][k], acc[ai][bj][m][n], 0, 0, 0); __builtin_amdgcn_s_setprio(0); } while (0)
; #define PG8_WAIT_V(n) asm volatile("s_waitcnt vmcnt(" #n ")" ::: "memory")
; #define PG8_WAIT_L(n) asm volatile("s_waitcnt lgkmcnt(" #n ")" ::: "memory")
; #define PG8_BAR __builtin_amdgcn_s_barrier()
; #define PG8_SCHED __builtin_amdgcn_sched_barrier(0)
; template <class Epi, class Sched, bool ALIGN_EPI = false, bool SP2 = false>
; __device__ __forceinline__ void gemm_phase(PG8_LAS unsigned char* lds, const Gemm g, const Sched& S, const Epi& E, const int tid_in) {
;     ...
;             PG8_LDA(At, 1, 1); PG8_STAGE(PG8_SB(1, 0), b3, voffB); PG8_STAGE(PG8_SB(1, 1), b3 + hstep, voffB); PG8_STAGE(PG8_SA(1, 0), a3, voffA);
;             PG8_WAIT_V(8); PG8_WAIT_L(0); PG8_BAR; PG8_MMA(1, 0, At, B0); PG8_MMA(1, 1, At, B1); PG8_BAR; PG8_SCHED;
	s_add_i32 s12, s61, s41
	v_lshl_add_u64 v[160:161], v[160:161], 0, s[92:93]
	s_mov_b32 m0, s12
	ds_read_b128 v[186:189], v168 offset:49152
	ds_read_b128 v[200:203], v168 offset:50176
	ds_read_b128 v[204:207], v168 offset:51200
	ds_read_b128 v[208:211], v168 offset:52224
	ds_read_b128 v[212:215], v168 offset:53248
	ds_read_b128 v[234:237], v168 offset:54272
	ds_read_b128 v[238:241], v168 offset:55296
	ds_read_b128 v[242:245], v168 offset:56320
	global_load_lds_dwordx4 v[160:161], off
	s_add_i32 m0, s12, 0x2000
	s_add_u32 s10, s10, 0x40080
	v_lshl_add_u64 v[160:161], v[190:191], 0, s[92:93]
	s_addc_u32 s11, s11, 0
	s_add_i32 s12, s62, s41
	global_load_lds_dwordx4 v[160:161], off
	v_lshl_add_u64 v[160:161], s[10:11], 0, v[148:149]
	s_mov_b32 m0, s12
	s_nop 0
	global_load_lds_dwordx4 v[160:161], off
	v_lshl_add_u64 v[160:161], s[10:11], 0, v[144:145]
	s_add_i32 m0, s12, 0x2000
	s_nop 0
	global_load_lds_dwordx4 v[160:161], off
	v_lshl_add_u64 v[160:161], v[218:219], 0, s[92:93]
	s_mov_b32 m0, s54
	s_nop 0
	global_load_lds_dwordx4 v[160:161], off
	v_lshl_add_u64 v[160:161], v[220:221], 0, s[92:93]
	s_mov_b32 m0, s55
	s_nop 0
	global_load_lds_dwordx4 v[160:161], off
	s_waitcnt vmcnt(8)
	s_waitcnt lgkmcnt(0)
	s_barrier
	s_setprio 1
	s_waitcnt lgkmcnt(0)
	v_mfma_f32_16x16x32_bf16 v[72:75], v[56:59], v[186:189], v[72:75]
	v_mfma_f32_16x16x32_bf16 v[60:63], v[68:71], v[186:189], v[60:63]
	v_mfma_f32_16x16x32_bf16 v[44:47], v[56:59], v[204:207], v[44:47]
	v_mfma_f32_16x16x32_bf16 v[40:43], v[68:71], v[204:207], v[40:43]
	v_mfma_f32_16x16x32_bf16 v[28:31], v[56:59], v[212:215], v[28:31]
	v_mfma_f32_16x16x32_bf16 v[24:27], v[68:71], v[212:215], v[24:27]
	v_mfma_f32_16x16x32_bf16 v[12:15], v[56:59], v[238:241], v[12:15]
	v_mfma_f32_16x16x32_bf16 v[8:11], v[68:71], v[238:241], v[8:11]
	v_mfma_f32_16x16x32_bf16 v[72:75], v[64:67], v[200:203], v[72:75]
	v_mfma_f32_16x16x32_bf16 v[60:63], v[76:79], v[200:203], v[60:63]
	v_mfma_f32_16x16x32_bf16 v[44:47], v[64:67], v[208:211], v[44:47]
	v_mfma_f32_16x16x32_bf16 v[40:43], v[76:79], v[208:211], v[40:43]
	v_mfma_f32_16x16x32_bf16 v[28:31], v[64:67], v[234:237], v[28:31]
	v_mfma_f32_16x16x32_bf16 v[24:27], v[76:79], v[234:237], v[24:27]
	v_mfma_f32_16x16x32_bf16 v[12:15], v[64:67], v[242:245], v[12:15]
	v_mfma_f32_16x16x32_bf16 v[8:11], v[76:79], v[242:245], v[8:11]
	v_mfma_f32_16x16x32_bf16 v[52:55], v[170:173], v[186:189], v[52:55]
	v_mfma_f32_16x16x32_bf16 v[48:51], v[178:181], v[186:189], v[48:51]
	v_mfma_f32_16x16x32_bf16 v[36:39], v[170:173], v[204:207], v[36:39]
	v_mfma_f32_16x16x32_bf16 v[32:35], v[178:181], v[204:207], v[32:35]
	v_mfma_f32_16x16x32_bf16 v[20:23], v[170:173], v[212:215], v[20:23]
	v_mfma_f32_16x16x32_bf16 v[16:19], v[178:181], v[212:215], v[16:19]
	v_mfma_f32_16x16x32_bf16 v[4:7], v[170:173], v[238:241], v[4:7]
	v_mfma_f32_16x16x32_bf16 v[0:3], v[178:181], v[238:241], v[0:3]
	v_mfma_f32_16x16x32_bf16 v[52:55], v[174:177], v[200:203], v[52:55]
	v_mfma_f32_16x16x32_bf16 v[48:51], v[182:185], v[200:203], v[48:51]
	v_mfma_f32_16x16x32_bf16 v[36:39], v[174:177], v[208:211], v[36:39]
	v_mfma_f32_16x16x32_bf16 v[32:35], v[182:185], v[208:211], v[32:35]
	v_mfma_f32_16x16x32_bf16 v[20:23], v[174:177], v[234:237], v[20:23]
	v_mfma_f32_16x16x32_bf16 v[16:19], v[182:185], v[234:237], v[16:19]
	v_mfma_f32_16x16x32_bf16 v[4:7], v[174:177], v[242:245], v[4:7]
	v_mfma_f32_16x16x32_bf16 v[0:3], v[182:185], v[242:245], v[0:3]
	s_setprio 0
	s_barrier
	s_add_i32 s60, s60, 2
	s_add_u32 s4, s4, 0x100
	s_addc_u32 s5, s5, 0
	s_add_u32 s58, s58, 0x100
	s_addc_u32 s59, s59, 0
	s_cmp_gt_u32 s60, 13
	s_cbranch_scc0 .LBB0_42
	s_and_b64 vcc, exec, s[34:35]
	s_cbranch_vccz .LBB0_45
	s_barrier

; #define PG8_STAGE(bufoff, gbase, voff) do { _Pragma("unroll") for (int _i = 0; _i < 2; ++_i) \
;         __builtin_amdgcn_global_load_lds((const unsigned*)((const char*)(gbase) + (voff)[_i]), (PG8_LAS unsigned*)(lds + (bufoff) + ldsw + _i * 8192), 16, 0, 0); } while (0)
; #define PG8_LDA(dst, b, h) do { _Pragma("unroll") for (int m = 0; m < 4; ++m) _Pragma("unroll") for (int k = 0; k < 2; ++k) dst[m][k] = *(const PG8_LAS bf16x8*)(lds + PG8_SA(b, h) + aoff + m * 2048 + k * 1024); } while (0)
; #define PG8_LDB(dst, b, h) do { _Pragma("unroll") for (int n = 0; n < 2; ++n) _Pragma("unroll") for (int k = 0; k < 2; ++k) dst[n][k] = *(const PG8_LAS bf16x8*)(lds + PG8_SB(b, h) + boff + n * 2048 + k * 1024); } while (0)
; #define PG8_MMA(ai, bj, At, Bt) do { __builtin_amdgcn_s_setprio(1); _Pragma("unroll") for (int m = 0; m < 4; ++m) _Pragma("unroll") for (int n = 0; n < 2; ++n) _Pragma("unroll") for (int k = 0; k < 2; ++k) \
;         acc[ai][bj][m][n] = __builtin_amdgcn_mfma_f32_16x16x32_bf16(Bt[n][k], At[m][k], acc[ai][bj][m][n], 0, 0, 0); __builtin_amdgcn_s_setprio(0); } while (0)
; #define PG8_WAIT_V(n) asm volatile("s_waitcnt vmcnt(" #n ")" ::: "memory")
; #define PG8_WAIT_L(n) asm volatile("s_waitcnt lgkmcnt(" #n ")" ::: "memory")
; #define PG8_BAR __builtin_amdgcn_s_barrier()
; #define PG8_SCHED __builtin_amdgcn_sched_barrier(0)
; template <class Epi, class Sched, bool ALIGN_EPI = false, bool SP2 = false>
; __device__ __forceinline__ void gemm_phase(PG8_LAS unsigned char* lds, const Gemm g, const Sched& S, const Epi& E, const int tid_in) {
;     ...
;             PG8_LDB(B0, 0, 0); PG8_LDB(B1, 0, 1); PG8_SCHED; PG8_LDA(At, 0, 0); PG8_STAGE(PG8_SA(1, 1), a1 + hstep, voffA);
;             PG8_WAIT_V(8); PG8_WAIT_L(0); PG8_BAR; PG8_MMA(0, 0, At, B0); PG8_MMA(0, 1, At, B1); PG8_BAR; PG8_SCHED;
;             PG8_LDA(At, 0, 1); PG8_STAGE(PG8_SB(0, 0), b2, voffB); PG8_STAGE(PG8_SB(0, 1), b2 + hstep, voffB); PG8_STAGE(PG8_SA(0, 0), a2, voffA);
.LBB0_284:
	s_add_i32 s52, s26, 2
	s_add_u32 s53, s24, 0x80
	s_addc_u32 s27, s25, 0
	s_add_i32 s56, 0, 0x10000
	s_cmp_eq_u32 s28, s26
	s_cselect_b32 s27, s21, s27
	s_cselect_b32 s26, s20, s53
	s_cselect_b32 s55, s23, s51
	s_cselect_b32 s54, s22, s29
	s_add_i32 s53, 0, 0x14000
	v_add_u32_e32 v154, s56, v143
	v_add_u32_e32 v170, s53, v143
	ds_read_b128 v[138:141], v154
	ds_read_b128 v[146:149], v154 offset:1024
	ds_read_b128 v[150:153], v154 offset:2048
	ds_read_b128 v[154:157], v154 offset:3072
	ds_read_b128 v[158:161], v170
	ds_read_b128 v[162:165], v170 offset:1024
	ds_read_b128 v[166:169], v170 offset:2048
	ds_read_b128 v[170:173], v170 offset:3072
	v_lshl_add_u64 v[190:191], s[24:25], 0, v[134:135]
	s_add_i32 m0, s38, 0xc000
	ds_read_b128 v[174:177], v145
	ds_read_b128 v[178:181], v145 offset:1024
	ds_read_b128 v[182:185], v145 offset:2048
	ds_read_b128 v[186:189], v145 offset:3072
	ds_read_b128 v[200:203], v145 offset:4096
	ds_read_b128 v[204:207], v145 offset:5120
	ds_read_b128 v[208:211], v145 offset:6144
	ds_read_b128 v[212:215], v145 offset:7168
	global_load_lds_dwordx4 v[190:191], off
	v_lshl_add_u64 v[190:191], s[24:25], 0, v[136:137]
	s_add_i32 m0, s38, 0xe000
	s_nop 0
	global_load_lds_dwordx4 v[190:191], off
	s_waitcnt vmcnt(8)
	s_waitcnt lgkmcnt(0)
	s_barrier
	s_setprio 1
	s_waitcnt lgkmcnt(0)
	v_mfma_f32_16x16x32_bf16 v[124:127], v[138:141], v[174:177], v[124:127]
	v_mfma_f32_16x16x32_bf16 v[120:123], v[150:153], v[174:177], v[120:123]
	v_mfma_f32_16x16x32_bf16 v[108:111], v[138:141], v[182:185], v[108:111]
	v_mfma_f32_16x16x32_bf16 v[104:107], v[150:153], v[182:185], v[104:107]
	v_mfma_f32_16x16x32_bf16 v[92:95], v[138:141], v[200:203], v[92:95]
	v_mfma_f32_16x16x32_bf16 v[88:91], v[150:153], v[200:203], v[88:91]
	v_mfma_f32_16x16x32_bf16 v[76:79], v[138:141], v[208:211], v[76:79]
	v_mfma_f32_16x16x32_bf16 v[72:75], v[150:153], v[208:211], v[72:75]
	v_mfma_f32_16x16x32_bf16 v[124:127], v[146:149], v[178:181], v[124:127]
	v_mfma_f32_16x16x32_bf16 v[120:123], v[154:157], v[178:181], v[120:123]
	v_mfma_f32_16x16x32_bf16 v[108:111], v[146:149], v[186:189], v[108:111]
	v_mfma_f32_16x16x32_bf16 v[104:107], v[154:157], v[186:189], v[104:107]
	v_mfma_f32_16x16x32_bf16 v[92:95], v[146:149], v[204:207], v[92:95]
	v_mfma_f32_16x16x32_bf16 v[88:91], v[154:157], v[204:207], v[88:91]
	v_mfma_f32_16x16x32_bf16 v[76:79], v[146:149], v[212:215], v[76:79]
	v_mfma_f32_16x16x32_bf16 v[72:75], v[154:157], v[212:215], v[72:75]
	v_mfma_f32_16x16x32_bf16 v[116:119], v[158:161], v[174:177], v[116:119]
	v_mfma_f32_16x16x32_bf16 v[112:115], v[166:169], v[174:177], v[112:115]
	v_mfma_f32_16x16x32_bf16 v[100:103], v[158:161], v[182:185], v[100:103]
	v_mfma_f32_16x16x32_bf16 v[96:99], v[166:169], v[182:185], v[96:99]
	v_mfma_f32_16x16x32_bf16 v[84:87], v[158:161], v[200:203], v[84:87]
	v_mfma_f32_16x16x32_bf16 v[80:83], v[166:169], v[200:203], v[80:83]
	v_mfma_f32_16x16x32_bf16 v[68:71], v[158:161], v[208:211], v[68:71]
	v_mfma_f32_16x16x32_bf16 v[64:67], v[166:169], v[208:211], v[64:67]
	v_mfma_f32_16x16x32_bf16 v[116:119], v[162:165], v[178:181], v[116:119]
	v_mfma_f32_16x16x32_bf16 v[112:115], v[170:173], v[178:181], v[112:115]
	v_mfma_f32_16x16x32_bf16 v[100:103], v[162:165], v[186:189], v[100:103]
	v_mfma_f32_16x16x32_bf16 v[96:99], v[170:173], v[186:189], v[96:99]
	v_mfma_f32_16x16x32_bf16 v[84:87], v[162:165], v[204:207], v[84:87]
	v_mfma_f32_16x16x32_bf16 v[80:83], v[170:173], v[204:207], v[80:83]
	v_mfma_f32_16x16x32_bf16 v[68:71], v[162:165], v[212:215], v[68:71]
	v_mfma_f32_16x16x32_bf16 v[64:67], v[170:173], v[212:215], v[64:67]
	s_setprio 0
	s_barrier
	s_add_i32 s56, s56, s35
	v_lshl_add_u64 v[190:191], s[54:55], 0, v[192:193]
	s_mov_b32 m0, s56
	ds_read_b128 v[174:177], v145 offset:16384
	ds_read_b128 v[178:181], v145 offset:17408
	ds_read_b128 v[182:185], v145 offset:18432
	ds_read_b128 v[186:189], v145 offset:19456
	ds_read_b128 v[200:203], v145 offset:20480
	ds_read_b128 v[204:207], v145 offset:21504
	ds_read_b128 v[208:211], v145 offset:22528
	ds_read_b128 v[212:215], v145 offset:23552
	global_load_lds_dwordx4 v[190:191], off
	s_add_i32 m0, s56, 0x2000
	v_lshl_add_u64 v[218:219], s[54:55], 0, v[132:133]
	s_add_u32 s54, s54, s12
	s_addc_u32 s55, s55, 0
	s_add_i32 s53, s53, s35
	global_load_lds_dwordx4 v[218:219], off
	v_lshl_add_u64 v[220:221], s[54:55], 0, v[192:193]
	s_mov_b32 m0, s53
	v_lshl_add_u64 v[230:231], s[54:55], 0, v[132:133]
	global_load_lds_dwordx4 v[220:221], off
	s_add_i32 m0, s53, 0x2000
	v_lshl_add_u64 v[232:233], s[26:27], 0, v[128:129]
	global_load_lds_dwordx4 v[230:231], off
	s_mov_b32 m0, s38
	v_lshl_add_u64 v[234:235], s[26:27], 0, v[130:131]
	global_load_lds_dwordx4 v[232:233], off
	s_mov_b32 m0, s39
	s_nop 0
	global_load_lds_dwordx4 v[234:235], off
	s_waitcnt vmcnt(8)
	s_waitcnt lgkmcnt(0)
	s_barrier
; #define PG8_STAGE(bufoff, gbase, voff) do { _Pragma("unroll") for (int _i = 0; _i < 2; ++_i) \
;         __builtin_amdgcn_global_load_lds((const unsigned*)((const char*)(gbase) + (voff)[_i]), (PG8_LAS unsigned*)(lds + (bufoff) + ldsw + _i * 8192), 16, 0, 0); } while (0)
; #define PG8_LDA(dst, b, h) do { _Pragma("unroll") for (int m = 0; m < 4; ++m) _Pragma("unroll") for (int k = 0; k < 2; ++k) dst[m][k] = *(const PG8_LAS bf16x8*)(lds + PG8_SA(b, h) + aoff + m * 2048 + k * 1024); } while (0)
; #define PG8_LDB(dst, b, h) do { _Pragma("unroll") for (int n = 0; n < 2; ++n) _Pragma("unroll") for (int k = 0; k < 2; ++k) dst[n][k] = *(const PG8_LAS bf16x8*)(lds + PG8_SB(b, h) + boff + n * 2048 + k * 1024); } while (0)
; #define PG8_MMA(ai, bj, At, Bt) do { __builtin_amdgcn_s_setprio(1); _Pragma("unroll") for (int m = 0; m < 4; ++m) _Pragma("unroll") for (int n = 0; n < 2; ++n) _Pragma("unroll") for (int k = 0; k < 2; ++k) \
;         acc[ai][bj][m][n] = __builtin_amdgcn_mfma_f32_16x16x32_bf16(Bt[n][k], At[m][k], acc[ai][bj][m][n], 0, 0, 0); __builtin_amdgcn_s_setprio(0); } while (0)
; #define PG8_WAIT_V(n) asm volatile("s_waitcnt vmcnt(" #n ")" ::: "memory")
; #define PG8_WAIT_L(n) asm volatile("s_waitcnt lgkmcnt(" #n ")" ::: "memory")
; #define PG8_BAR __builtin_amdgcn_s_barrier()
; #define PG8_SCHED __builtin_amdgcn_sched_barrier(0)
; template <class Epi, class Sched, bool ALIGN_EPI = false, bool SP2 = false>
; __device__ __forceinline__ void gemm_phase(PG8_LAS unsigned char* lds, const Gemm g, const Sched& S, const Epi& E, const int tid_in) {
;     ...
;             PG8_WAIT_V(8); PG8_WAIT_L(0); PG8_BAR; PG8_MMA(1, 0, At, B0); PG8_MMA(1, 1, At, B1); PG8_BAR; PG8_SCHED;
;             PG8_LDB(B0, 1, 0); PG8_LDB(B1, 1, 1); PG8_SCHED; PG8_LDA(At, 1, 0); PG8_STAGE(PG8_SA(0, 1), a2 + hstep, voffA);
;             PG8_WAIT_V(8); PG8_WAIT_L(0); PG8_BAR; PG8_MMA(0, 0, At, B0); PG8_MMA(0, 1, At, B1); PG8_BAR; PG8_SCHED;
	s_setprio 1
	s_waitcnt lgkmcnt(0)
	v_mfma_f32_16x16x32_bf16 v[60:63], v[138:141], v[174:177], v[60:63]
	v_mfma_f32_16x16x32_bf16 v[56:59], v[150:153], v[174:177], v[56:59]
	v_mfma_f32_16x16x32_bf16 v[44:47], v[138:141], v[182:185], v[44:47]
	v_mfma_f32_16x16x32_bf16 v[40:43], v[150:153], v[182:185], v[40:43]
	v_mfma_f32_16x16x32_bf16 v[28:31], v[138:141], v[200:203], v[28:31]
	v_mfma_f32_16x16x32_bf16 v[24:27], v[150:153], v[200:203], v[24:27]
	v_mfma_f32_16x16x32_bf16 v[12:15], v[138:141], v[208:211], v[12:15]
	v_mfma_f32_16x16x32_bf16 v[8:11], v[150:153], v[208:211], v[8:11]
	v_mfma_f32_16x16x32_bf16 v[60:63], v[146:149], v[178:181], v[60:63]
	v_mfma_f32_16x16x32_bf16 v[56:59], v[154:157], v[178:181], v[56:59]
	v_mfma_f32_16x16x32_bf16 v[44:47], v[146:149], v[186:189], v[44:47]
	v_mfma_f32_16x16x32_bf16 v[40:43], v[154:157], v[186:189], v[40:43]
	v_mfma_f32_16x16x32_bf16 v[28:31], v[146:149], v[204:207], v[28:31]
	v_mfma_f32_16x16x32_bf16 v[24:27], v[154:157], v[204:207], v[24:27]
	v_mfma_f32_16x16x32_bf16 v[12:15], v[146:149], v[212:215], v[12:15]
	v_mfma_f32_16x16x32_bf16 v[8:11], v[154:157], v[212:215], v[8:11]
	v_mfma_f32_16x16x32_bf16 v[52:55], v[158:161], v[174:177], v[52:55]
	v_mfma_f32_16x16x32_bf16 v[48:51], v[166:169], v[174:177], v[48:51]
	v_mfma_f32_16x16x32_bf16 v[36:39], v[158:161], v[182:185], v[36:39]
	v_mfma_f32_16x16x32_bf16 v[32:35], v[166:169], v[182:185], v[32:35]
	v_mfma_f32_16x16x32_bf16 v[20:23], v[158:161], v[200:203], v[20:23]
	v_mfma_f32_16x16x32_bf16 v[16:19], v[166:169], v[200:203], v[16:19]
	v_mfma_f32_16x16x32_bf16 v[4:7], v[158:161], v[208:211], v[4:7]
	v_mfma_f32_16x16x32_bf16 v[0:3], v[166:169], v[208:211], v[0:3]
	v_mfma_f32_16x16x32_bf16 v[52:55], v[162:165], v[178:181], v[52:55]
	v_mfma_f32_16x16x32_bf16 v[48:51], v[170:173], v[178:181], v[48:51]
	v_mfma_f32_16x16x32_bf16 v[36:39], v[162:165], v[186:189], v[36:39]
	v_mfma_f32_16x16x32_bf16 v[32:35], v[170:173], v[186:189], v[32:35]
	v_mfma_f32_16x16x32_bf16 v[20:23], v[162:165], v[204:207], v[20:23]
	v_mfma_f32_16x16x32_bf16 v[16:19], v[170:173], v[204:207], v[16:19]
	v_mfma_f32_16x16x32_bf16 v[4:7], v[162:165], v[212:215], v[4:7]
	v_mfma_f32_16x16x32_bf16 v[0:3], v[170:173], v[212:215], v[0:3]
	s_setprio 0
	s_barrier
	s_add_i32 s53, 0, 0x18000
	s_add_i32 s54, 0, 0x1c000
	v_add_u32_e32 v154, s53, v143
	v_add_u32_e32 v170, s54, v143
	ds_read_b128 v[138:141], v154
	ds_read_b128 v[146:149], v154 offset:1024
	ds_read_b128 v[150:153], v154 offset:2048
	ds_read_b128 v[154:157], v154 offset:3072
	ds_read_b128 v[158:161], v170
	ds_read_b128 v[162:165], v170 offset:1024
	ds_read_b128 v[166:169], v170 offset:2048
	ds_read_b128 v[170:173], v170 offset:3072
	s_add_u32 s26, s26, s12
	s_addc_u32 s27, s27, 0
	s_mov_b32 m0, s40
	v_lshl_add_u64 v[236:237], s[26:27], 0, v[128:129]
	ds_read_b128 v[174:177], v145 offset:32768
	ds_read_b128 v[178:181], v145 offset:33792
	ds_read_b128 v[182:185], v145 offset:34816
	ds_read_b128 v[186:189], v145 offset:35840
	ds_read_b128 v[200:203], v145 offset:36864
	ds_read_b128 v[204:207], v145 offset:37888
	ds_read_b128 v[208:211], v145 offset:38912
	ds_read_b128 v[212:215], v145 offset:39936
	global_load_lds_dwordx4 v[236:237], off
	v_lshl_add_u64 v[236:237], s[26:27], 0, v[130:131]
	s_mov_b32 m0, s41
	s_nop 0
	global_load_lds_dwordx4 v[236:237], off
	s_waitcnt vmcnt(8)
	s_waitcnt lgkmcnt(0)
	s_barrier
	s_setprio 1
	s_waitcnt lgkmcnt(0)
	v_mfma_f32_16x16x32_bf16 v[124:127], v[138:141], v[174:177], v[124:127]
	v_mfma_f32_16x16x32_bf16 v[120:123], v[150:153], v[174:177], v[120:123]
	v_mfma_f32_16x16x32_bf16 v[108:111], v[138:141], v[182:185], v[108:111]
	v_mfma_f32_16x16x32_bf16 v[104:107], v[150:153], v[182:185], v[104:107]
	v_mfma_f32_16x16x32_bf16 v[92:95], v[138:141], v[200:203], v[92:95]
	v_mfma_f32_16x16x32_bf16 v[88:91], v[150:153], v[200:203], v[88:91]
	v_mfma_f32_16x16x32_bf16 v[76:79], v[138:141], v[208:211], v[76:79]
	v_mfma_f32_16x16x32_bf16 v[72:75], v[150:153], v[208:211], v[72:75]
	v_mfma_f32_16x16x32_bf16 v[124:127], v[146:149], v[178:181], v[124:127]
	v_mfma_f32_16x16x32_bf16 v[120:123], v[154:157], v[178:181], v[120:123]
	v_mfma_f32_16x16x32_bf16 v[108:111], v[146:149], v[186:189], v[108:111]
	v_mfma_f32_16x16x32_bf16 v[104:107], v[154:157], v[186:189], v[104:107]
	v_mfma_f32_16x16x32_bf16 v[92:95], v[146:149], v[204:207], v[92:95]
	v_mfma_f32_16x16x32_bf16 v[88:91], v[154:157], v[204:207], v[88:91]
	v_mfma_f32_16x16x32_bf16 v[76:79], v[146:149], v[212:215], v[76:79]
	v_mfma_f32_16x16x32_bf16 v[72:75], v[154:157], v[212:215], v[72:75]
	v_mfma_f32_16x16x32_bf16 v[116:119], v[158:161], v[174:177], v[116:119]
	v_mfma_f32_16x16x32_bf16 v[112:115], v[166:169], v[174:177], v[112:115]
	v_mfma_f32_16x16x32_bf16 v[100:103], v[158:161], v[182:185], v[100:103]
	v_mfma_f32_16x16x32_bf16 v[96:99], v[166:169], v[182:185], v[96:99]
	v_mfma_f32_16x16x32_bf16 v[84:87], v[158:161], v[200:203], v[84:87]
	v_mfma_f32_16x16x32_bf16 v[80:83], v[166:169], v[200:203], v[80:83]
	v_mfma_f32_16x16x32_bf16 v[68:71], v[158:161], v[208:211], v[68:71]
	v_mfma_f32_16x16x32_bf16 v[64:67], v[166:169], v[208:211], v[64:67]
	v_mfma_f32_16x16x32_bf16 v[116:119], v[162:165], v[178:181], v[116:119]
	v_mfma_f32_16x16x32_bf16 v[112:115], v[170:173], v[178:181], v[112:115]
	v_mfma_f32_16x16x32_bf16 v[100:103], v[162:165], v[186:189], v[100:103]
	v_mfma_f32_16x16x32_bf16 v[96:99], v[170:173], v[186:189], v[96:99]
	v_mfma_f32_16x16x32_bf16 v[84:87], v[162:165], v[204:207], v[84:87]
	v_mfma_f32_16x16x32_bf16 v[80:83], v[170:173], v[204:207], v[80:83]
	v_mfma_f32_16x16x32_bf16 v[68:71], v[162:165], v[212:215], v[68:71]
	v_mfma_f32_16x16x32_bf16 v[64:67], v[170:173], v[212:215], v[64:67]
	s_setprio 0
	s_barrier
; #define PG8_STAGE(bufoff, gbase, voff) do { _Pragma("unroll") for (int _i = 0; _i < 2; ++_i) \
;         __builtin_amdgcn_global_load_lds((const unsigned*)((const char*)(gbase) + (voff)[_i]), (PG8_LAS unsigned*)(lds + (bufoff) + ldsw + _i * 8192), 16, 0, 0); } while (0)
; #define PG8_LDA(dst, b, h) do { _Pragma("unroll") for (int m = 0; m < 4; ++m) _Pragma("unroll") for (int k = 0; k < 2; ++k) dst[m][k] = *(const PG8_LAS bf16x8*)(lds + PG8_SA(b, h) + aoff + m * 2048 + k * 1024); } while (0)
; #define PG8_MMA(ai, bj, At, Bt) do { __builtin_amdgcn_s_setprio(1); _Pragma("unroll") for (int m = 0; m < 4; ++m) _Pragma("unroll") for (int n = 0; n < 2; ++n) _Pragma("unroll") for (int k = 0; k < 2; ++k) \
;         acc[ai][bj][m][n] = __builtin_amdgcn_mfma_f32_16x16x32_bf16(Bt[n][k], At[m][k], acc[ai][bj][m][n], 0, 0, 0); __builtin_amdgcn_s_setprio(0); } while (0)
; #define PG8_WAIT_V(n) asm volatile("s_waitcnt vmcnt(" #n ")" ::: "memory")
; #define PG8_WAIT_L(n) asm volatile("s_waitcnt lgkmcnt(" #n ")" ::: "memory")
; #define PG8_BAR __builtin_amdgcn_s_barrier()
; #define PG8_SCHED __builtin_amdgcn_sched_barrier(0)
; template <class Epi, class Sched, bool ALIGN_EPI = false, bool SP2 = false>
; __device__ __forceinline__ void gemm_phase(PG8_LAS unsigned char* lds, const Gemm g, const Sched& S, const Epi& E, const int tid_in) {
;     ...
;             PG8_LDA(At, 1, 1); PG8_STAGE(PG8_SB(1, 0), b3, voffB); PG8_STAGE(PG8_SB(1, 1), b3 + hstep, voffB); PG8_STAGE(PG8_SA(1, 0), a3, voffA);
;             PG8_WAIT_V(8); PG8_WAIT_L(0); PG8_BAR; PG8_MMA(1, 0, At, B0); PG8_MMA(1, 1, At, B1); PG8_BAR; PG8_SCHED;
	s_add_i32 s26, s53, s35
	v_lshl_add_u64 v[190:191], v[190:191], 0, s[92:93]
	s_mov_b32 m0, s26
	ds_read_b128 v[174:177], v145 offset:49152
	ds_read_b128 v[178:181], v145 offset:50176
	ds_read_b128 v[182:185], v145 offset:51200
	ds_read_b128 v[186:189], v145 offset:52224
	ds_read_b128 v[200:203], v145 offset:53248
	ds_read_b128 v[204:207], v145 offset:54272
	ds_read_b128 v[208:211], v145 offset:55296
	ds_read_b128 v[212:215], v145 offset:56320
	global_load_lds_dwordx4 v[190:191], off
	v_lshl_add_u64 v[190:191], v[218:219], 0, s[92:93]
	s_add_i32 m0, s26, 0x2000
	s_add_i32 s26, s54, s35
	global_load_lds_dwordx4 v[190:191], off
	v_lshl_add_u64 v[190:191], v[220:221], 0, s[92:93]
	s_mov_b32 m0, s26
	s_nop 0
	global_load_lds_dwordx4 v[190:191], off
	v_lshl_add_u64 v[190:191], v[230:231], 0, s[92:93]
	s_add_i32 m0, s26, 0x2000
	s_nop 0
	global_load_lds_dwordx4 v[190:191], off
	v_lshl_add_u64 v[190:191], v[232:233], 0, s[92:93]
	s_mov_b32 m0, s42
	s_nop 0
	global_load_lds_dwordx4 v[190:191], off
	v_lshl_add_u64 v[190:191], v[234:235], 0, s[92:93]
	s_mov_b32 m0, s43
	s_nop 0
	global_load_lds_dwordx4 v[190:191], off
	s_waitcnt vmcnt(8)
	s_waitcnt lgkmcnt(0)
	s_barrier
	s_setprio 1
	s_waitcnt lgkmcnt(0)
	v_mfma_f32_16x16x32_bf16 v[60:63], v[138:141], v[174:177], v[60:63]
	v_mfma_f32_16x16x32_bf16 v[56:59], v[150:153], v[174:177], v[56:59]
	v_mfma_f32_16x16x32_bf16 v[44:47], v[138:141], v[182:185], v[44:47]
	v_mfma_f32_16x16x32_bf16 v[40:43], v[150:153], v[182:185], v[40:43]
	v_mfma_f32_16x16x32_bf16 v[28:31], v[138:141], v[200:203], v[28:31]
	v_mfma_f32_16x16x32_bf16 v[24:27], v[150:153], v[200:203], v[24:27]
	v_mfma_f32_16x16x32_bf16 v[12:15], v[138:141], v[208:211], v[12:15]
	v_mfma_f32_16x16x32_bf16 v[8:11], v[150:153], v[208:211], v[8:11]
	v_mfma_f32_16x16x32_bf16 v[60:63], v[146:149], v[178:181], v[60:63]
	v_mfma_f32_16x16x32_bf16 v[56:59], v[154:157], v[178:181], v[56:59]
	v_mfma_f32_16x16x32_bf16 v[44:47], v[146:149], v[186:189], v[44:47]
	v_mfma_f32_16x16x32_bf16 v[40:43], v[154:157], v[186:189], v[40:43]
	v_mfma_f32_16x16x32_bf16 v[28:31], v[146:149], v[204:207], v[28:31]
	v_mfma_f32_16x16x32_bf16 v[24:27], v[154:157], v[204:207], v[24:27]
	v_mfma_f32_16x16x32_bf16 v[12:15], v[146:149], v[212:215], v[12:15]
	v_mfma_f32_16x16x32_bf16 v[8:11], v[154:157], v[212:215], v[8:11]
	v_mfma_f32_16x16x32_bf16 v[52:55], v[158:161], v[174:177], v[52:55]
	v_mfma_f32_16x16x32_bf16 v[48:51], v[166:169], v[174:177], v[48:51]
	v_mfma_f32_16x16x32_bf16 v[36:39], v[158:161], v[182:185], v[36:39]
	v_mfma_f32_16x16x32_bf16 v[32:35], v[166:169], v[182:185], v[32:35]
	v_mfma_f32_16x16x32_bf16 v[20:23], v[158:161], v[200:203], v[20:23]
	v_mfma_f32_16x16x32_bf16 v[16:19], v[166:169], v[200:203], v[16:19]
	v_mfma_f32_16x16x32_bf16 v[4:7], v[158:161], v[208:211], v[4:7]
	v_mfma_f32_16x16x32_bf16 v[0:3], v[166:169], v[208:211], v[0:3]
	v_mfma_f32_16x16x32_bf16 v[52:55], v[162:165], v[178:181], v[52:55]
	v_mfma_f32_16x16x32_bf16 v[48:51], v[170:173], v[178:181], v[48:51]
	v_mfma_f32_16x16x32_bf16 v[36:39], v[162:165], v[186:189], v[36:39]
	v_mfma_f32_16x16x32_bf16 v[32:35], v[170:173], v[186:189], v[32:35]
	v_mfma_f32_16x16x32_bf16 v[20:23], v[162:165], v[204:207], v[20:23]
	v_mfma_f32_16x16x32_bf16 v[16:19], v[170:173], v[204:207], v[16:19]
	v_mfma_f32_16x16x32_bf16 v[4:7], v[162:165], v[212:215], v[4:7]
	v_mfma_f32_16x16x32_bf16 v[0:3], v[170:173], v[212:215], v[0:3]
	s_setprio 0
	s_barrier
	s_add_u32 s24, s24, 0x100
	s_addc_u32 s25, s25, 0
	s_add_u32 s29, s29, 0x100
	s_addc_u32 s51, s51, 0
	s_cmp_ge_u32 s52, s50
	s_mov_b32 s26, s52
	s_cbranch_scc0 .LBB0_284
	s_and_b64 vcc, exec, s[16:17]
	s_cbranch_vccz .LBB0_287

; #define PG8_STAGE(bufoff, gbase, voff) do { _Pragma("unroll") for (int _i = 0; _i < 2; ++_i) \
;         __builtin_amdgcn_global_load_lds((const unsigned*)((const char*)(gbase) + (voff)[_i]), (PG8_LAS unsigned*)(lds + (bufoff) + ldsw + _i * 8192), 16, 0, 0); } while (0)
; #define PG8_LDA(dst, b, h) do { _Pragma("unroll") for (int m = 0; m < 4; ++m) _Pragma("unroll") for (int k = 0; k < 2; ++k) dst[m][k] = *(const PG8_LAS bf16x8*)(lds + PG8_SA(b, h) + aoff + m * 2048 + k * 1024); } while (0)
; #define PG8_LDB(dst, b, h) do { _Pragma("unroll") for (int n = 0; n < 2; ++n) _Pragma("unroll") for (int k = 0; k < 2; ++k) dst[n][k] = *(const PG8_LAS bf16x8*)(lds + PG8_SB(b, h) + boff + n * 2048 + k * 1024); } while (0)
; #define PG8_MMA(ai, bj, At, Bt) do { __builtin_amdgcn_s_setprio(1); _Pragma("unroll") for (int m = 0; m < 4; ++m) _Pragma("unroll") for (int n = 0; n < 2; ++n) _Pragma("unroll") for (int k = 0; k < 2; ++k) \
;         acc[ai][bj][m][n] = __builtin_amdgcn_mfma_f32_16x16x32_bf16(Bt[n][k], At[m][k], acc[ai][bj][m][n], 0, 0, 0); __builtin_amdgcn_s_setprio(0); } while (0)
; #define PG8_WAIT_V(n) asm volatile("s_waitcnt vmcnt(" #n ")" ::: "memory")
; #define PG8_WAIT_L(n) asm volatile("s_waitcnt lgkmcnt(" #n ")" ::: "memory")
; #define PG8_BAR __builtin_amdgcn_s_barrier()
; #define PG8_SCHED __builtin_amdgcn_sched_barrier(0)
; template <class Epi, class Sched, bool ALIGN_EPI = false, bool SP2 = false>
; __device__ __forceinline__ void gemm_phase(PG8_LAS unsigned char* lds, const Gemm g, const Sched& S, const Epi& E, const int tid_in) {
;     ...
;             PG8_LDB(B0, 0, 0); PG8_LDB(B1, 0, 1); PG8_SCHED; PG8_LDA(At, 0, 0); PG8_STAGE(PG8_SA(1, 1), a1 + hstep, voffA);
;             PG8_WAIT_V(8); PG8_WAIT_L(0); PG8_BAR; PG8_MMA(0, 0, At, B0); PG8_MMA(0, 1, At, B1); PG8_BAR; PG8_SCHED;
;             PG8_LDA(At, 0, 1); PG8_STAGE(PG8_SB(0, 0), b2, voffB); PG8_STAGE(PG8_SB(0, 1), b2 + hstep, voffB); PG8_STAGE(PG8_SA(0, 0), a2, voffA);
.LBB0_307:
	s_add_u32 s20, s4, 0xfffc0080
	s_addc_u32 s21, s5, -1
	s_add_i32 s44, 0, 0x10000
	s_cmp_eq_u32 s43, 12
	s_cselect_b32 s23, s11, s21
	s_cselect_b32 s22, s39, s20
	s_cselect_b32 s21, s9, s42
	s_cselect_b32 s20, s40, s41
	s_add_i32 s46, 0, 0x14000
	v_add_u32_e32 v154, s44, v143
	v_add_u32_e32 v170, s46, v143
	ds_read_b128 v[138:141], v154
	ds_read_b128 v[146:149], v154 offset:1024
	ds_read_b128 v[150:153], v154 offset:2048
	ds_read_b128 v[154:157], v154 offset:3072
	ds_read_b128 v[158:161], v170
	ds_read_b128 v[162:165], v170 offset:1024
	ds_read_b128 v[166:169], v170 offset:2048
	ds_read_b128 v[170:173], v170 offset:3072
	v_lshl_add_u64 v[190:191], s[4:5], 0, v[134:135]
	s_add_i32 m0, s30, 0xc000
	ds_read_b128 v[174:177], v145
	ds_read_b128 v[178:181], v145 offset:1024
	ds_read_b128 v[182:185], v145 offset:2048
	ds_read_b128 v[186:189], v145 offset:3072
	ds_read_b128 v[200:203], v145 offset:4096
	ds_read_b128 v[204:207], v145 offset:5120
	ds_read_b128 v[208:211], v145 offset:6144
	ds_read_b128 v[212:215], v145 offset:7168
	global_load_lds_dwordx4 v[190:191], off
	v_lshl_add_u64 v[190:191], s[4:5], 0, v[136:137]
	s_add_i32 m0, s30, 0xe000
	s_nop 0
	global_load_lds_dwordx4 v[190:191], off
	s_waitcnt vmcnt(8)
	s_waitcnt lgkmcnt(0)
	s_barrier
	s_setprio 1
	s_waitcnt lgkmcnt(0)
	v_mfma_f32_16x16x32_bf16 v[124:127], v[138:141], v[174:177], v[124:127]
	v_mfma_f32_16x16x32_bf16 v[116:119], v[150:153], v[174:177], v[116:119]
	v_mfma_f32_16x16x32_bf16 v[108:111], v[138:141], v[182:185], v[108:111]
	v_mfma_f32_16x16x32_bf16 v[100:103], v[150:153], v[182:185], v[100:103]
	v_mfma_f32_16x16x32_bf16 v[92:95], v[138:141], v[200:203], v[92:95]
	v_mfma_f32_16x16x32_bf16 v[84:87], v[150:153], v[200:203], v[84:87]
	v_mfma_f32_16x16x32_bf16 v[76:79], v[138:141], v[208:211], v[76:79]
	v_mfma_f32_16x16x32_bf16 v[68:71], v[150:153], v[208:211], v[68:71]
	v_mfma_f32_16x16x32_bf16 v[124:127], v[146:149], v[178:181], v[124:127]
	v_mfma_f32_16x16x32_bf16 v[116:119], v[154:157], v[178:181], v[116:119]
	v_mfma_f32_16x16x32_bf16 v[108:111], v[146:149], v[186:189], v[108:111]
	v_mfma_f32_16x16x32_bf16 v[100:103], v[154:157], v[186:189], v[100:103]
	v_mfma_f32_16x16x32_bf16 v[92:95], v[146:149], v[204:207], v[92:95]
	v_mfma_f32_16x16x32_bf16 v[84:87], v[154:157], v[204:207], v[84:87]
	v_mfma_f32_16x16x32_bf16 v[76:79], v[146:149], v[212:215], v[76:79]
	v_mfma_f32_16x16x32_bf16 v[68:71], v[154:157], v[212:215], v[68:71]
	v_mfma_f32_16x16x32_bf16 v[120:123], v[158:161], v[174:177], v[120:123]
	v_mfma_f32_16x16x32_bf16 v[112:115], v[166:169], v[174:177], v[112:115]
	v_mfma_f32_16x16x32_bf16 v[104:107], v[158:161], v[182:185], v[104:107]
	v_mfma_f32_16x16x32_bf16 v[96:99], v[166:169], v[182:185], v[96:99]
	v_mfma_f32_16x16x32_bf16 v[88:91], v[158:161], v[200:203], v[88:91]
	v_mfma_f32_16x16x32_bf16 v[80:83], v[166:169], v[200:203], v[80:83]
	v_mfma_f32_16x16x32_bf16 v[72:75], v[158:161], v[208:211], v[72:75]
	v_mfma_f32_16x16x32_bf16 v[64:67], v[166:169], v[208:211], v[64:67]
	v_mfma_f32_16x16x32_bf16 v[120:123], v[162:165], v[178:181], v[120:123]
	v_mfma_f32_16x16x32_bf16 v[112:115], v[170:173], v[178:181], v[112:115]
	v_mfma_f32_16x16x32_bf16 v[104:107], v[162:165], v[186:189], v[104:107]
	v_mfma_f32_16x16x32_bf16 v[96:99], v[170:173], v[186:189], v[96:99]
	v_mfma_f32_16x16x32_bf16 v[88:91], v[162:165], v[204:207], v[88:91]
	v_mfma_f32_16x16x32_bf16 v[80:83], v[170:173], v[204:207], v[80:83]
	v_mfma_f32_16x16x32_bf16 v[72:75], v[162:165], v[212:215], v[72:75]
	v_mfma_f32_16x16x32_bf16 v[64:67], v[170:173], v[212:215], v[64:67]
	s_setprio 0
	s_barrier
	s_add_i32 s44, s44, s27
	v_lshl_add_u64 v[190:191], s[20:21], 0, v[192:193]
	s_mov_b32 m0, s44
	ds_read_b128 v[174:177], v145 offset:16384
	ds_read_b128 v[178:181], v145 offset:17408
	ds_read_b128 v[182:185], v145 offset:18432
	ds_read_b128 v[186:189], v145 offset:19456
	ds_read_b128 v[200:203], v145 offset:20480
	ds_read_b128 v[204:207], v145 offset:21504
	ds_read_b128 v[208:211], v145 offset:22528
	ds_read_b128 v[212:215], v145 offset:23552
	global_load_lds_dwordx4 v[190:191], off
	s_add_i32 m0, s44, 0x2000
	s_add_u32 s44, s20, 0x40000
	v_lshl_add_u64 v[218:219], s[20:21], 0, v[128:129]
	s_addc_u32 s45, s21, 0
	s_add_i32 s46, s46, s27
	global_load_lds_dwordx4 v[218:219], off
	v_lshl_add_u64 v[220:221], s[44:45], 0, v[192:193]
	s_mov_b32 m0, s46
	v_lshl_add_u64 v[230:231], s[22:23], 0, v[130:131]
	global_load_lds_dwordx4 v[220:221], off
	v_lshl_add_u64 v[220:221], s[44:45], 0, v[128:129]
	s_add_i32 m0, s46, 0x2000
	s_nop 0
	global_load_lds_dwordx4 v[220:221], off
	v_lshl_add_u64 v[220:221], s[22:23], 0, v[132:133]
	s_mov_b32 m0, s30
	s_nop 0
	global_load_lds_dwordx4 v[220:221], off
	s_mov_b32 m0, s31
	s_nop 0
	global_load_lds_dwordx4 v[230:231], off
	s_waitcnt vmcnt(8)
	s_waitcnt lgkmcnt(0)
	s_barrier
; #define PG8_STAGE(bufoff, gbase, voff) do { _Pragma("unroll") for (int _i = 0; _i < 2; ++_i) \
;         __builtin_amdgcn_global_load_lds((const unsigned*)((const char*)(gbase) + (voff)[_i]), (PG8_LAS unsigned*)(lds + (bufoff) + ldsw + _i * 8192), 16, 0, 0); } while (0)
; #define PG8_LDA(dst, b, h) do { _Pragma("unroll") for (int m = 0; m < 4; ++m) _Pragma("unroll") for (int k = 0; k < 2; ++k) dst[m][k] = *(const PG8_LAS bf16x8*)(lds + PG8_SA(b, h) + aoff + m * 2048 + k * 1024); } while (0)
; #define PG8_LDB(dst, b, h) do { _Pragma("unroll") for (int n = 0; n < 2; ++n) _Pragma("unroll") for (int k = 0; k < 2; ++k) dst[n][k] = *(const PG8_LAS bf16x8*)(lds + PG8_SB(b, h) + boff + n * 2048 + k * 1024); } while (0)
; #define PG8_MMA(ai, bj, At, Bt) do { __builtin_amdgcn_s_setprio(1); _Pragma("unroll") for (int m = 0; m < 4; ++m) _Pragma("unroll") for (int n = 0; n < 2; ++n) _Pragma("unroll") for (int k = 0; k < 2; ++k) \
;         acc[ai][bj][m][n] = __builtin_amdgcn_mfma_f32_16x16x32_bf16(Bt[n][k], At[m][k], acc[ai][bj][m][n], 0, 0, 0); __builtin_amdgcn_s_setprio(0); } while (0)
; #define PG8_WAIT_V(n) asm volatile("s_waitcnt vmcnt(" #n ")" ::: "memory")
; #define PG8_WAIT_L(n) asm volatile("s_waitcnt lgkmcnt(" #n ")" ::: "memory")
; #define PG8_BAR __builtin_amdgcn_s_barrier()
; #define PG8_SCHED __builtin_amdgcn_sched_barrier(0)
; template <class Epi, class Sched, bool ALIGN_EPI = false, bool SP2 = false>
; __device__ __forceinline__ void gemm_phase(PG8_LAS unsigned char* lds, const Gemm g, const Sched& S, const Epi& E, const int tid_in) {
;     ...
;             PG8_WAIT_V(8); PG8_WAIT_L(0); PG8_BAR; PG8_MMA(1, 0, At, B0); PG8_MMA(1, 1, At, B1); PG8_BAR; PG8_SCHED;
;             PG8_LDB(B0, 1, 0); PG8_LDB(B1, 1, 1); PG8_SCHED; PG8_LDA(At, 1, 0); PG8_STAGE(PG8_SA(0, 1), a2 + hstep, voffA);
;             PG8_WAIT_V(8); PG8_WAIT_L(0); PG8_BAR; PG8_MMA(0, 0, At, B0); PG8_MMA(0, 1, At, B1); PG8_BAR; PG8_SCHED;
	s_setprio 1
	s_waitcnt lgkmcnt(0)
	v_mfma_f32_16x16x32_bf16 v[60:63], v[138:141], v[174:177], v[60:63]
	v_mfma_f32_16x16x32_bf16 v[52:55], v[150:153], v[174:177], v[52:55]
	v_mfma_f32_16x16x32_bf16 v[44:47], v[138:141], v[182:185], v[44:47]
	v_mfma_f32_16x16x32_bf16 v[36:39], v[150:153], v[182:185], v[36:39]
	v_mfma_f32_16x16x32_bf16 v[28:31], v[138:141], v[200:203], v[28:31]
	v_mfma_f32_16x16x32_bf16 v[20:23], v[150:153], v[200:203], v[20:23]
	v_mfma_f32_16x16x32_bf16 v[12:15], v[138:141], v[208:211], v[12:15]
	v_mfma_f32_16x16x32_bf16 v[4:7], v[150:153], v[208:211], v[4:7]
	v_mfma_f32_16x16x32_bf16 v[60:63], v[146:149], v[178:181], v[60:63]
	v_mfma_f32_16x16x32_bf16 v[52:55], v[154:157], v[178:181], v[52:55]
	v_mfma_f32_16x16x32_bf16 v[44:47], v[146:149], v[186:189], v[44:47]
	v_mfma_f32_16x16x32_bf16 v[36:39], v[154:157], v[186:189], v[36:39]
	v_mfma_f32_16x16x32_bf16 v[28:31], v[146:149], v[204:207], v[28:31]
	v_mfma_f32_16x16x32_bf16 v[20:23], v[154:157], v[204:207], v[20:23]
	v_mfma_f32_16x16x32_bf16 v[12:15], v[146:149], v[212:215], v[12:15]
	v_mfma_f32_16x16x32_bf16 v[4:7], v[154:157], v[212:215], v[4:7]
	v_mfma_f32_16x16x32_bf16 v[56:59], v[158:161], v[174:177], v[56:59]
	v_mfma_f32_16x16x32_bf16 v[48:51], v[166:169], v[174:177], v[48:51]
	v_mfma_f32_16x16x32_bf16 v[40:43], v[158:161], v[182:185], v[40:43]
	v_mfma_f32_16x16x32_bf16 v[32:35], v[166:169], v[182:185], v[32:35]
	v_mfma_f32_16x16x32_bf16 v[24:27], v[158:161], v[200:203], v[24:27]
	v_mfma_f32_16x16x32_bf16 v[16:19], v[166:169], v[200:203], v[16:19]
	v_mfma_f32_16x16x32_bf16 v[8:11], v[158:161], v[208:211], v[8:11]
	v_mfma_f32_16x16x32_bf16 v[0:3], v[166:169], v[208:211], v[0:3]
	v_mfma_f32_16x16x32_bf16 v[56:59], v[162:165], v[178:181], v[56:59]
	v_mfma_f32_16x16x32_bf16 v[48:51], v[170:173], v[178:181], v[48:51]
	v_mfma_f32_16x16x32_bf16 v[40:43], v[162:165], v[186:189], v[40:43]
	v_mfma_f32_16x16x32_bf16 v[32:35], v[170:173], v[186:189], v[32:35]
	v_mfma_f32_16x16x32_bf16 v[24:27], v[162:165], v[204:207], v[24:27]
	v_mfma_f32_16x16x32_bf16 v[16:19], v[170:173], v[204:207], v[16:19]
	v_mfma_f32_16x16x32_bf16 v[8:11], v[162:165], v[212:215], v[8:11]
	v_mfma_f32_16x16x32_bf16 v[0:3], v[170:173], v[212:215], v[0:3]
	s_setprio 0
	s_barrier
	s_add_i32 s44, 0, 0x18000
	s_add_i32 s45, 0, 0x1c000
	v_add_u32_e32 v154, s44, v143
	v_add_u32_e32 v170, s45, v143
	ds_read_b128 v[138:141], v154
	ds_read_b128 v[146:149], v154 offset:1024
	ds_read_b128 v[150:153], v154 offset:2048
	ds_read_b128 v[154:157], v154 offset:3072
	ds_read_b128 v[158:161], v170
	ds_read_b128 v[162:165], v170 offset:1024
	ds_read_b128 v[166:169], v170 offset:2048
	ds_read_b128 v[170:173], v170 offset:3072
	s_add_u32 s22, s22, 0x40000
	s_addc_u32 s23, s23, 0
	s_mov_b32 m0, s34
	v_lshl_add_u64 v[232:233], s[22:23], 0, v[132:133]
	ds_read_b128 v[174:177], v145 offset:32768
	ds_read_b128 v[178:181], v145 offset:33792
	ds_read_b128 v[182:185], v145 offset:34816
	ds_read_b128 v[186:189], v145 offset:35840
	ds_read_b128 v[200:203], v145 offset:36864
	ds_read_b128 v[204:207], v145 offset:37888
	ds_read_b128 v[208:211], v145 offset:38912
	ds_read_b128 v[212:215], v145 offset:39936
	global_load_lds_dwordx4 v[232:233], off
	v_lshl_add_u64 v[232:233], s[22:23], 0, v[130:131]
	s_mov_b32 m0, s35
	s_nop 0
	global_load_lds_dwordx4 v[232:233], off
	s_waitcnt vmcnt(8)
	s_waitcnt lgkmcnt(0)
	s_barrier
	s_setprio 1
	s_waitcnt lgkmcnt(0)
	v_mfma_f32_16x16x32_bf16 v[124:127], v[138:141], v[174:177], v[124:127]
	v_mfma_f32_16x16x32_bf16 v[116:119], v[150:153], v[174:177], v[116:119]
	v_mfma_f32_16x16x32_bf16 v[108:111], v[138:141], v[182:185], v[108:111]
	v_mfma_f32_16x16x32_bf16 v[100:103], v[150:153], v[182:185], v[100:103]
	v_mfma_f32_16x16x32_bf16 v[92:95], v[138:141], v[200:203], v[92:95]
	v_mfma_f32_16x16x32_bf16 v[84:87], v[150:153], v[200:203], v[84:87]
	v_mfma_f32_16x16x32_bf16 v[76:79], v[138:141], v[208:211], v[76:79]
	v_mfma_f32_16x16x32_bf16 v[68:71], v[150:153], v[208:211], v[68:71]
	v_mfma_f32_16x16x32_bf16 v[124:127], v[146:149], v[178:181], v[124:127]
	v_mfma_f32_16x16x32_bf16 v[116:119], v[154:157], v[178:181], v[116:119]
	v_mfma_f32_16x16x32_bf16 v[108:111], v[146:149], v[186:189], v[108:111]
	v_mfma_f32_16x16x32_bf16 v[100:103], v[154:157], v[186:189], v[100:103]
	v_mfma_f32_16x16x32_bf16 v[92:95], v[146:149], v[204:207], v[92:95]
	v_mfma_f32_16x16x32_bf16 v[84:87], v[154:157], v[204:207], v[84:87]
	v_mfma_f32_16x16x32_bf16 v[76:79], v[146:149], v[212:215], v[76:79]
	v_mfma_f32_16x16x32_bf16 v[68:71], v[154:157], v[212:215], v[68:71]
	v_mfma_f32_16x16x32_bf16 v[120:123], v[158:161], v[174:177], v[120:123]
	v_mfma_f32_16x16x32_bf16 v[112:115], v[166:169], v[174:177], v[112:115]
	v_mfma_f32_16x16x32_bf16 v[104:107], v[158:161], v[182:185], v[104:107]
	v_mfma_f32_16x16x32_bf16 v[96:99], v[166:169], v[182:185], v[96:99]
	v_mfma_f32_16x16x32_bf16 v[88:91], v[158:161], v[200:203], v[88:91]
	v_mfma_f32_16x16x32_bf16 v[80:83], v[166:169], v[200:203], v[80:83]
	v_mfma_f32_16x16x32_bf16 v[72:75], v[158:161], v[208:211], v[72:75]
	v_mfma_f32_16x16x32_bf16 v[64:67], v[166:169], v[208:211], v[64:67]
	v_mfma_f32_16x16x32_bf16 v[120:123], v[162:165], v[178:181], v[120:123]
	v_mfma_f32_16x16x32_bf16 v[112:115], v[170:173], v[178:181], v[112:115]
	v_mfma_f32_16x16x32_bf16 v[104:107], v[162:165], v[186:189], v[104:107]
	v_mfma_f32_16x16x32_bf16 v[96:99], v[170:173], v[186:189], v[96:99]
	v_mfma_f32_16x16x32_bf16 v[88:91], v[162:165], v[204:207], v[88:91]
	v_mfma_f32_16x16x32_bf16 v[80:83], v[170:173], v[204:207], v[80:83]
	v_mfma_f32_16x16x32_bf16 v[72:75], v[162:165], v[212:215], v[72:75]
	v_mfma_f32_16x16x32_bf16 v[64:67], v[170:173], v[212:215], v[64:67]
	s_setprio 0
	s_barrier
; #define PG8_STAGE(bufoff, gbase, voff) do { _Pragma("unroll") for (int _i = 0; _i < 2; ++_i) \
;         __builtin_amdgcn_global_load_lds((const unsigned*)((const char*)(gbase) + (voff)[_i]), (PG8_LAS unsigned*)(lds + (bufoff) + ldsw + _i * 8192), 16, 0, 0); } while (0)
; #define PG8_LDA(dst, b, h) do { _Pragma("unroll") for (int m = 0; m < 4; ++m) _Pragma("unroll") for (int k = 0; k < 2; ++k) dst[m][k] = *(const PG8_LAS bf16x8*)(lds + PG8_SA(b, h) + aoff + m * 2048 + k * 1024); } while (0)
; #define PG8_MMA(ai, bj, At, Bt) do { __builtin_amdgcn_s_setprio(1); _Pragma("unroll") for (int m = 0; m < 4; ++m) _Pragma("unroll") for (int n = 0; n < 2; ++n) _Pragma("unroll") for (int k = 0; k < 2; ++k) \
;         acc[ai][bj][m][n] = __builtin_amdgcn_mfma_f32_16x16x32_bf16(Bt[n][k], At[m][k], acc[ai][bj][m][n], 0, 0, 0); __builtin_amdgcn_s_setprio(0); } while (0)
; #define PG8_WAIT_V(n) asm volatile("s_waitcnt vmcnt(" #n ")" ::: "memory")
; #define PG8_WAIT_L(n) asm volatile("s_waitcnt lgkmcnt(" #n ")" ::: "memory")
; #define PG8_BAR __builtin_amdgcn_s_barrier()
; #define PG8_SCHED __builtin_amdgcn_sched_barrier(0)
; template <class Epi, class Sched, bool ALIGN_EPI = false, bool SP2 = false>
; __device__ __forceinline__ void gemm_phase(PG8_LAS unsigned char* lds, const Gemm g, const Sched& S, const Epi& E, const int tid_in) {
;     ...
;             PG8_LDA(At, 1, 1); PG8_STAGE(PG8_SB(1, 0), b3, voffB); PG8_STAGE(PG8_SB(1, 1), b3 + hstep, voffB); PG8_STAGE(PG8_SA(1, 0), a3, voffA);
;             PG8_WAIT_V(8); PG8_WAIT_L(0); PG8_BAR; PG8_MMA(1, 0, At, B0); PG8_MMA(1, 1, At, B1); PG8_BAR; PG8_SCHED;
	s_add_i32 s22, s44, s27
	v_lshl_add_u64 v[190:191], v[190:191], 0, s[92:93]
	s_mov_b32 m0, s22
	ds_read_b128 v[174:177], v145 offset:49152
	ds_read_b128 v[178:181], v145 offset:50176
	ds_read_b128 v[182:185], v145 offset:51200
	ds_read_b128 v[186:189], v145 offset:52224
	ds_read_b128 v[200:203], v145 offset:53248
	ds_read_b128 v[204:207], v145 offset:54272
	ds_read_b128 v[208:211], v145 offset:55296
	ds_read_b128 v[212:215], v145 offset:56320
	global_load_lds_dwordx4 v[190:191], off
	s_add_i32 m0, s22, 0x2000
	s_add_u32 s20, s20, 0x40080
	v_lshl_add_u64 v[190:191], v[218:219], 0, s[92:93]
	s_addc_u32 s21, s21, 0
	s_add_i32 s22, s45, s27
	global_load_lds_dwordx4 v[190:191], off
	v_lshl_add_u64 v[190:191], s[20:21], 0, v[192:193]
	s_mov_b32 m0, s22
	s_nop 0
	global_load_lds_dwordx4 v[190:191], off
	v_lshl_add_u64 v[190:191], s[20:21], 0, v[128:129]
	s_add_i32 m0, s22, 0x2000
	s_nop 0
	global_load_lds_dwordx4 v[190:191], off
	v_lshl_add_u64 v[190:191], v[220:221], 0, s[92:93]
	s_mov_b32 m0, s36
	s_nop 0
	global_load_lds_dwordx4 v[190:191], off
	v_lshl_add_u64 v[190:191], v[230:231], 0, s[92:93]
	s_mov_b32 m0, s37
	s_nop 0
	global_load_lds_dwordx4 v[190:191], off
	s_waitcnt vmcnt(8)
	s_waitcnt lgkmcnt(0)
	s_barrier
	s_setprio 1
	s_waitcnt lgkmcnt(0)
	v_mfma_f32_16x16x32_bf16 v[60:63], v[138:141], v[174:177], v[60:63]
	v_mfma_f32_16x16x32_bf16 v[52:55], v[150:153], v[174:177], v[52:55]
	v_mfma_f32_16x16x32_bf16 v[44:47], v[138:141], v[182:185], v[44:47]
	v_mfma_f32_16x16x32_bf16 v[36:39], v[150:153], v[182:185], v[36:39]
	v_mfma_f32_16x16x32_bf16 v[28:31], v[138:141], v[200:203], v[28:31]
	v_mfma_f32_16x16x32_bf16 v[20:23], v[150:153], v[200:203], v[20:23]
	v_mfma_f32_16x16x32_bf16 v[12:15], v[138:141], v[208:211], v[12:15]
	v_mfma_f32_16x16x32_bf16 v[4:7], v[150:153], v[208:211], v[4:7]
	v_mfma_f32_16x16x32_bf16 v[60:63], v[146:149], v[178:181], v[60:63]
	v_mfma_f32_16x16x32_bf16 v[52:55], v[154:157], v[178:181], v[52:55]
	v_mfma_f32_16x16x32_bf16 v[44:47], v[146:149], v[186:189], v[44:47]
	v_mfma_f32_16x16x32_bf16 v[36:39], v[154:157], v[186:189], v[36:39]
	v_mfma_f32_16x16x32_bf16 v[28:31], v[146:149], v[204:207], v[28:31]
	v_mfma_f32_16x16x32_bf16 v[20:23], v[154:157], v[204:207], v[20:23]
	v_mfma_f32_16x16x32_bf16 v[12:15], v[146:149], v[212:215], v[12:15]
	v_mfma_f32_16x16x32_bf16 v[4:7], v[154:157], v[212:215], v[4:7]
	v_mfma_f32_16x16x32_bf16 v[56:59], v[158:161], v[174:177], v[56:59]
	v_mfma_f32_16x16x32_bf16 v[48:51], v[166:169], v[174:177], v[48:51]
	v_mfma_f32_16x16x32_bf16 v[40:43], v[158:161], v[182:185], v[40:43]
	v_mfma_f32_16x16x32_bf16 v[32:35], v[166:169], v[182:185], v[32:35]
	v_mfma_f32_16x16x32_bf16 v[24:27], v[158:161], v[200:203], v[24:27]
	v_mfma_f32_16x16x32_bf16 v[16:19], v[166:169], v[200:203], v[16:19]
	v_mfma_f32_16x16x32_bf16 v[8:11], v[158:161], v[208:211], v[8:11]
	v_mfma_f32_16x16x32_bf16 v[0:3], v[166:169], v[208:211], v[0:3]
	v_mfma_f32_16x16x32_bf16 v[56:59], v[162:165], v[178:181], v[56:59]
	v_mfma_f32_16x16x32_bf16 v[48:51], v[170:173], v[178:181], v[48:51]
	v_mfma_f32_16x16x32_bf16 v[40:43], v[162:165], v[186:189], v[40:43]
	v_mfma_f32_16x16x32_bf16 v[32:35], v[170:173], v[186:189], v[32:35]
	v_mfma_f32_16x16x32_bf16 v[24:27], v[162:165], v[204:207], v[24:27]
	v_mfma_f32_16x16x32_bf16 v[16:19], v[170:173], v[204:207], v[16:19]
	v_mfma_f32_16x16x32_bf16 v[8:11], v[162:165], v[212:215], v[8:11]
	v_mfma_f32_16x16x32_bf16 v[0:3], v[170:173], v[212:215], v[0:3]
	s_setprio 0
	s_barrier
	s_add_i32 s43, s43, 2
	s_add_u32 s4, s4, 0x100
	s_addc_u32 s5, s5, 0
	s_add_u32 s41, s41, 0x100
	s_addc_u32 s42, s42, 0
	s_cmp_gt_u32 s43, 13
	s_cbranch_scc0 .LBB0_307
	s_and_b64 vcc, exec, s[18:19]
	s_cbranch_vccz .LBB0_310
	s_barrier
